# drop the per-unit vmcnt(0) in G4/G5/G6 that only guarded the old in-epilogue ss loads (now hoisted into spare registers)
# speedup vs baseline: 1.0216x; 1.0007x over previous
; template <class Epi, class Sched, bool ALIGN_EPI = false, bool SP2 = false>
; __device__ __forceinline__ void gemm_phase(PG8_LAS unsigned char* lds, const Gemm g, const Sched& S, const Epi& E) {
;     ...
;         const bool has_next = S.next(ui + 1, nxt);
;         const char* nA = has_next ? (const char*)g.A + (size_t)nxt.pm * tstep : cA; const char* nB = has_next ? (const char*)g.Bt + (size_t)nxt.pn * tstep : cB;
;         for (int t = 0; t < nt; t += 2) {
;             const bool last = (t == nt - 2);
;             const char* a1 = cA + (size_t)(t + 1) * kstep;
;             const char* a2 = last ? nA : cA + (size_t)(t + 2) * kstep; const char* b2 = last ? nB : cB + (size_t)(t + 2) * kstep;
;             const char* a3 = a2 + kstep; const char* b3 = b2 + kstep;
;     ...
; #pragma unroll
;         for (int a = 0; a < 2; ++a)
; #pragma unroll
;             for (int b = 0; b < 2; ++b)
; #pragma unroll
;                 for (int m = 0; m < 4; ++m)
; #pragma unroll
;                     for (int n = 0; n < 2; ++n) acc[a][b][m][n] = (f32x4){0.f, 0.f, 0.f, 0.f};
;         cur = nxt; cA = nA; cB = nB; ++ui;
.LBB0_1222:
	s_ashr_i32 s23, s22, 31
	s_lshl_b64 s[24:25], s[22:23], 19
	s_add_u32 s24, s42, s24
	s_addc_u32 s25, s43, s25
	s_and_b64 s[26:27], s[6:7], exec
	s_cselect_b32 s23, s25, s35
	s_cselect_b32 s29, s24, s34
	s_ashr_i32 s21, s20, 31
	s_lshl_b64 s[26:27], s[20:21], 19
	s_add_u32 s26, s33, s26
	s_addc_u32 s27, s40, s27
	s_and_b64 s[38:39], s[6:7], exec
	s_cselect_b32 s21, s27, s37
	s_cselect_b32 s58, s26, s36
	s_add_u32 s34, s34, 0x40080
	s_addc_u32 s35, s35, 0
	s_add_u32 s59, s36, 0x100
	v_mov_b32_e32 v0, 0
	s_addc_u32 s60, s37, 0
	s_mov_b32 s61, -2
	s_waitcnt lgkmcnt(0)
	v_mov_b32_e32 v1, v0
	v_mov_b32_e32 v2, v0
	v_mov_b32_e32 v3, v0
	v_mov_b32_e32 v4, v0
	v_mov_b32_e32 v5, v0
	v_mov_b32_e32 v6, v0
	v_mov_b32_e32 v7, v0
	s_nop 0
	v_mov_b64_e32 v[16:17], 0
	v_mov_b64_e32 v[18:19], 0
	v_mov_b64_e32 v[20:21], 0
	v_mov_b64_e32 v[22:23], 0
	v_mov_b64_e32 v[32:33], 0
	v_mov_b64_e32 v[34:35], 0
	v_mov_b64_e32 v[36:37], 0
	v_mov_b64_e32 v[38:39], 0
	v_mov_b64_e32 v[48:49], 0
	v_mov_b64_e32 v[50:51], 0
	v_mov_b64_e32 v[52:53], 0
	v_mov_b64_e32 v[54:55], 0
	v_mov_b64_e32 v[8:9], 0
	v_mov_b64_e32 v[10:11], 0
	v_mov_b64_e32 v[12:13], 0
	v_mov_b64_e32 v[14:15], 0
	v_mov_b64_e32 v[24:25], 0
	v_mov_b64_e32 v[26:27], 0
	v_mov_b64_e32 v[28:29], 0
	v_mov_b64_e32 v[30:31], 0
	v_mov_b64_e32 v[40:41], 0
	v_mov_b64_e32 v[42:43], 0
	v_mov_b64_e32 v[44:45], 0
	v_mov_b64_e32 v[46:47], 0
	v_mov_b64_e32 v[56:57], 0
	v_mov_b64_e32 v[58:59], 0
	v_mov_b64_e32 v[60:61], 0
	v_mov_b64_e32 v[62:63], 0
	v_mov_b64_e32 v[64:65], 0
	v_mov_b64_e32 v[66:67], 0
	v_mov_b64_e32 v[68:69], 0
	v_mov_b64_e32 v[70:71], 0
	v_mov_b64_e32 v[80:81], 0
	v_mov_b64_e32 v[82:83], 0
	v_mov_b64_e32 v[84:85], 0
	v_mov_b64_e32 v[86:87], 0
	v_mov_b64_e32 v[96:97], 0
	v_mov_b64_e32 v[98:99], 0
	v_mov_b64_e32 v[100:101], 0
	v_mov_b64_e32 v[102:103], 0
	v_mov_b64_e32 v[112:113], 0
	v_mov_b64_e32 v[114:115], 0
	v_mov_b64_e32 v[116:117], 0
	v_mov_b64_e32 v[118:119], 0
	v_mov_b64_e32 v[72:73], 0
	v_mov_b64_e32 v[74:75], 0
	v_mov_b64_e32 v[76:77], 0
	v_mov_b64_e32 v[78:79], 0
	v_mov_b64_e32 v[88:89], 0
	v_mov_b64_e32 v[90:91], 0
	v_mov_b64_e32 v[92:93], 0
	v_mov_b64_e32 v[94:95], 0
	v_mov_b64_e32 v[104:105], 0
	v_mov_b64_e32 v[106:107], 0
	v_mov_b64_e32 v[108:109], 0
	v_mov_b64_e32 v[110:111], 0
	v_mov_b64_e32 v[120:121], 0
	v_mov_b64_e32 v[122:123], 0
	v_mov_b64_e32 v[124:125], 0
	v_mov_b64_e32 v[126:127], 0

; template <class Epi, class Sched, bool ALIGN_EPI = false, bool SP2 = false>
; __device__ __forceinline__ void gemm_phase(PG8_LAS unsigned char* lds, const Gemm g, const Sched& S, const Epi& E) {
;     ...
;         const bool has_next = S.next(ui + 1, nxt);
;         const char* nA = has_next ? (const char*)g.A + (size_t)nxt.pm * tstep : cA; const char* nB = has_next ? (const char*)g.Bt + (size_t)nxt.pn * tstep : cB;
;         for (int t = 0; t < nt; t += 2) {
;             const bool last = (t == nt - 2);
;             const char* a1 = cA + (size_t)(t + 1) * kstep;
;             const char* a2 = last ? nA : cA + (size_t)(t + 2) * kstep; const char* b2 = last ? nB : cB + (size_t)(t + 2) * kstep;
;             const char* a3 = a2 + kstep; const char* b3 = b2 + kstep;
;     ...
; #pragma unroll
;         for (int a = 0; a < 2; ++a)
; #pragma unroll
;             for (int b = 0; b < 2; ++b)
; #pragma unroll
;                 for (int m = 0; m < 4; ++m)
; #pragma unroll
;                     for (int n = 0; n < 2; ++n) acc[a][b][m][n] = (f32x4){0.f, 0.f, 0.f, 0.f};
;         cur = nxt; cA = nA; cB = nB; ++ui;
.LBB0_1309:
	s_ashr_i32 s21, s20, 31
	s_lshl_b64 s[22:23], s[20:21], 19
	s_add_u32 s22, s56, s22
	s_addc_u32 s23, s57, s23
	s_and_b64 s[24:25], s[4:5], exec
	s_cselect_b32 s21, s23, s27
	s_cselect_b32 s50, s22, s26
	s_ashr_i32 s19, s18, 31
	s_lshl_b64 s[24:25], s[18:19], 19
	s_add_u32 s24, s33, s24
	s_addc_u32 s25, s34, s25
	s_and_b64 s[30:31], s[4:5], exec
	s_cselect_b32 s19, s25, s29
	s_cselect_b32 s51, s24, s28
	s_add_u32 s26, s26, 0x40080
	s_addc_u32 s27, s27, 0
	s_add_u32 s52, s28, 0x100
	v_mov_b32_e32 v0, 0
	s_addc_u32 s53, s29, 0
	s_mov_b32 s58, -2
	v_mov_b32_e32 v1, v0
	v_mov_b32_e32 v2, v0
	v_mov_b32_e32 v3, v0
	v_mov_b32_e32 v4, v0
	v_mov_b32_e32 v5, v0
	v_mov_b32_e32 v6, v0
	v_mov_b32_e32 v7, v0
	s_nop 0
	v_mov_b64_e32 v[16:17], 0
	v_mov_b64_e32 v[18:19], 0
	v_mov_b64_e32 v[20:21], 0
	v_mov_b64_e32 v[22:23], 0
	v_mov_b64_e32 v[32:33], 0
	v_mov_b64_e32 v[34:35], 0
	v_mov_b64_e32 v[36:37], 0
	v_mov_b64_e32 v[38:39], 0
	v_mov_b64_e32 v[48:49], 0
	v_mov_b64_e32 v[50:51], 0
	v_mov_b64_e32 v[52:53], 0
	v_mov_b64_e32 v[54:55], 0
	v_mov_b64_e32 v[8:9], 0
	v_mov_b64_e32 v[10:11], 0
	v_mov_b64_e32 v[12:13], 0
	v_mov_b64_e32 v[14:15], 0
	v_mov_b64_e32 v[24:25], 0
	v_mov_b64_e32 v[26:27], 0
	v_mov_b64_e32 v[28:29], 0
	v_mov_b64_e32 v[30:31], 0
	v_mov_b64_e32 v[40:41], 0
	v_mov_b64_e32 v[42:43], 0
	v_mov_b64_e32 v[44:45], 0
	v_mov_b64_e32 v[46:47], 0
	v_mov_b64_e32 v[56:57], 0
	v_mov_b64_e32 v[58:59], 0
	v_mov_b64_e32 v[60:61], 0
	v_mov_b64_e32 v[62:63], 0
	v_mov_b64_e32 v[64:65], 0
	v_mov_b64_e32 v[66:67], 0
	v_mov_b64_e32 v[68:69], 0
	v_mov_b64_e32 v[70:71], 0
	v_mov_b64_e32 v[80:81], 0
	v_mov_b64_e32 v[82:83], 0
	v_mov_b64_e32 v[84:85], 0
	v_mov_b64_e32 v[86:87], 0
	v_mov_b64_e32 v[96:97], 0
	v_mov_b64_e32 v[98:99], 0
	v_mov_b64_e32 v[100:101], 0
	v_mov_b64_e32 v[102:103], 0
	v_mov_b64_e32 v[112:113], 0
	v_mov_b64_e32 v[114:115], 0
	v_mov_b64_e32 v[116:117], 0
	v_mov_b64_e32 v[118:119], 0
	v_mov_b64_e32 v[72:73], 0
	v_mov_b64_e32 v[74:75], 0
	v_mov_b64_e32 v[76:77], 0
	v_mov_b64_e32 v[78:79], 0
	v_mov_b64_e32 v[88:89], 0
	v_mov_b64_e32 v[90:91], 0
	v_mov_b64_e32 v[92:93], 0
	v_mov_b64_e32 v[94:95], 0
	v_mov_b64_e32 v[104:105], 0
	v_mov_b64_e32 v[106:107], 0
	v_mov_b64_e32 v[108:109], 0
	v_mov_b64_e32 v[110:111], 0
	v_mov_b64_e32 v[120:121], 0
	v_mov_b64_e32 v[122:123], 0
	v_mov_b64_e32 v[124:125], 0
	v_mov_b64_e32 v[126:127], 0

; template <class Epi, class Sched, bool ALIGN_EPI = false, bool SP2 = false>
; __device__ __forceinline__ void gemm_phase(PG8_LAS unsigned char* lds, const Gemm g, const Sched& S, const Epi& E) {
;     ...
;         for (int t = 0; t < nt; t += 2) {
;             const bool last = (t == nt - 2);
;             const char* a1 = cA + (size_t)(t + 1) * kstep;
;             const char* a2 = last ? nA : cA + (size_t)(t + 2) * kstep; const char* b2 = last ? nB : cB + (size_t)(t + 2) * kstep;
;             const char* a3 = a2 + kstep; const char* b3 = b2 + kstep;
;     ...
; #pragma unroll
;         for (int a = 0; a < 2; ++a)
; #pragma unroll
;             for (int b = 0; b < 2; ++b)
; #pragma unroll
;                 for (int m = 0; m < 4; ++m)
; #pragma unroll
;                     for (int n = 0; n < 2; ++n) acc[a][b][m][n] = (f32x4){0.f, 0.f, 0.f, 0.f};
;         cur = nxt; cA = nA; cB = nB; ++ui;
.LBB0_1394:
	s_add_u32 s6, s36, 0xb0080
	s_addc_u32 s7, s37, 0
	s_add_u32 s60, s34, 0x100
	v_mov_b32_e32 v0, 0
	s_addc_u32 s61, s35, 0
	s_mov_b32 s62, -2
	v_mov_b32_e32 v1, v0
	v_mov_b32_e32 v2, v0
	v_mov_b32_e32 v3, v0
	v_mov_b32_e32 v4, v0
	v_mov_b32_e32 v5, v0
	v_mov_b32_e32 v6, v0
	v_mov_b32_e32 v7, v0
	s_nop 0
	v_mov_b64_e32 v[12:13], 0
	v_mov_b64_e32 v[14:15], 0
	v_mov_b64_e32 v[20:21], 0
	v_mov_b64_e32 v[22:23], 0
	v_mov_b64_e32 v[28:29], 0
	v_mov_b64_e32 v[30:31], 0
	v_mov_b64_e32 v[36:37], 0
	v_mov_b64_e32 v[38:39], 0
	v_mov_b64_e32 v[48:49], 0
	v_mov_b64_e32 v[50:51], 0
	v_mov_b64_e32 v[52:53], 0
	v_mov_b64_e32 v[54:55], 0
	v_mov_b64_e32 v[8:9], 0
	v_mov_b64_e32 v[10:11], 0
	v_mov_b64_e32 v[16:17], 0
	v_mov_b64_e32 v[18:19], 0
	v_mov_b64_e32 v[24:25], 0
	v_mov_b64_e32 v[26:27], 0
	v_mov_b64_e32 v[32:33], 0
	v_mov_b64_e32 v[34:35], 0
	v_mov_b64_e32 v[40:41], 0
	v_mov_b64_e32 v[42:43], 0
	v_mov_b64_e32 v[44:45], 0
	v_mov_b64_e32 v[46:47], 0
	v_mov_b64_e32 v[56:57], 0
	v_mov_b64_e32 v[58:59], 0
	v_mov_b64_e32 v[60:61], 0
	v_mov_b64_e32 v[62:63], 0
	v_mov_b64_e32 v[64:65], 0
	v_mov_b64_e32 v[66:67], 0
	v_mov_b64_e32 v[68:69], 0
	v_mov_b64_e32 v[70:71], 0
	v_mov_b64_e32 v[76:77], 0
	v_mov_b64_e32 v[78:79], 0
	v_mov_b64_e32 v[84:85], 0
	v_mov_b64_e32 v[86:87], 0
	v_mov_b64_e32 v[92:93], 0
	v_mov_b64_e32 v[94:95], 0
	v_mov_b64_e32 v[100:101], 0
	v_mov_b64_e32 v[102:103], 0
	v_mov_b64_e32 v[112:113], 0
	v_mov_b64_e32 v[114:115], 0
	v_mov_b64_e32 v[116:117], 0
	v_mov_b64_e32 v[118:119], 0
	v_mov_b64_e32 v[72:73], 0
	v_mov_b64_e32 v[74:75], 0
	v_mov_b64_e32 v[80:81], 0
	v_mov_b64_e32 v[82:83], 0
	v_mov_b64_e32 v[88:89], 0
	v_mov_b64_e32 v[90:91], 0
	v_mov_b64_e32 v[96:97], 0
	v_mov_b64_e32 v[98:99], 0
	v_mov_b64_e32 v[104:105], 0
	v_mov_b64_e32 v[106:107], 0
	v_mov_b64_e32 v[108:109], 0
	v_mov_b64_e32 v[110:111], 0
	v_mov_b64_e32 v[120:121], 0
	v_mov_b64_e32 v[122:123], 0
	v_mov_b64_e32 v[124:125], 0
	v_mov_b64_e32 v[126:127], 0
